# v25 plus attention loop blocks in execution order (rescale blocks out of line, iteration-end blocks fall through)
# speedup vs baseline: 1.0019x; 1.0019x over previous
; #define DMA(slot, t) do { \
;     __builtin_amdgcn_global_load_lds((const unsigned*)(Kg + (long)(t) * (64 * 256)), (LAS unsigned*)(L3 + K_OFF + (slot) * SHM_T + wid * 1024), 16, 0, 0); \
;     __builtin_amdgcn_global_load_lds((const unsigned*)(Vg + (long)(t) * 8192), (LAS unsigned*)(L3 + (slot) * SHM_T + wid * 1024), 16, 0, 0); } while (0)
; #define BAR() do { asm volatile("s_waitcnt lgkmcnt(0)" ::: "memory"); __builtin_amdgcn_s_barrier(); asm volatile("" ::: "memory"); } while (0)
; #define WAITV(n) asm volatile("s_waitcnt vmcnt(" #n ")" ::: "memory")
; #define QKT(P0, P1, b) qkt(P0, P1, nm, K_lds + (b) * SHM_T, qr, ko, c00, c01, c10, c11)
; __device__ __forceinline__ void partialSM_first(f32x16& p0, f32x16& p1, f32x16& nm) {
;   const float delta = max32(p0, p1) - PSHIFT;
;   for (int r = 0; r < 16; ++r) { p0[r] -= delta; p1[r] -= delta; nm[r] -= delta; }
;   for (int r = 0; r < 16; ++r) p0[r] = __builtin_amdgcn_exp2f(p0[r]);
; }
; __device__ __forceinline__ void body(const unsigned char* Q8b, const unsigned char* K8h, const unsigned char* VT8h, const bf16_t* Gb, bf16_t* Ob, int seq, char* lds, const int wid, ...
;     ...
;   if (!pre) { DMA(0, 0); DMA(1, 1); } else BAR();
;   DMA(2, 2);
;   WAITV(2); BAR();
;   QKT(pA0, pA1, 0); partialSM_first(pA0, pA1, nm);
.LBB0_371:
	s_mov_b32 m0, s76
	v_lshl_add_u64 v[2:3], v[220:221], 0, s[42:43]
	global_load_lds_dwordx4 v[2:3], off
	v_lshl_add_u64 v[2:3], v[222:223], 0, s[38:39]
	s_mov_b32 m0, s78
	s_nop 0
	global_load_lds_dwordx4 v[2:3], off
	s_waitcnt vmcnt(2)
	s_waitcnt lgkmcnt(0)
	s_barrier
	ds_read_b128 v[22:25], v243 offset:32768
	ds_read_b128 v[18:21], v242 offset:32768
	ds_read_b128 v[34:37], v242 offset:36864
	ds_read_b128 v[38:41], v243 offset:36864
	v_mov_b64_e32 v[2:3], s[8:9]
	v_mov_b64_e32 v[4:5], s[10:11]
	v_mov_b64_e32 v[6:7], s[12:13]
	v_mov_b64_e32 v[8:9], s[14:15]
	v_mov_b64_e32 v[10:11], s[16:17]
	v_mov_b64_e32 v[12:13], s[18:19]
	v_mov_b64_e32 v[14:15], s[20:21]
	v_mov_b64_e32 v[16:17], s[22:23]
	s_nop 1
	s_waitcnt vmcnt(0) lgkmcnt(0)
	v_mfma_scale_f32_32x32x64_f8f6f4 v[18:33], v[18:25], v[176:183], v[2:17], v240, v239 op_sel_hi:[0,0,0]
	s_xor_b64 s[48:49], s[54:55], -1
	s_add_u32 s56, s56, s36
	s_addc_u32 s57, s57, 0
	v_lshl_add_u64 v[224:225], v[216:217], 0, s[58:59]
	v_lshl_add_u64 v[226:227], v[218:219], 0, s[56:57]
	s_mov_b32 s45, 0
	s_mov_b32 s47, 0
	v_mfma_scale_f32_32x32x64_f8f6f4 v[2:17], v[34:41], v[176:183], v[2:17], v240, v239 op_sel_hi:[0,0,0]
	ds_read_b128 v[38:41], v245 offset:32768
	ds_read_b128 v[34:37], v244 offset:32768
	ds_read_b128 v[42:45], v244 offset:36864
	ds_read_b128 v[46:49], v245 offset:36864
	s_waitcnt lgkmcnt(2)
	v_mfma_scale_f32_32x32x64_f8f6f4 v[18:33], v[34:41], v[184:191], v[18:33], v240, v239 op_sel_hi:[0,0,0]
	s_waitcnt lgkmcnt(0)
	v_mfma_scale_f32_32x32x64_f8f6f4 v[2:17], v[42:49], v[184:191], v[2:17], v240, v239 op_sel_hi:[0,0,0]
	s_nop 15
	s_nop 1
	v_max_f32_e32 v1, v19, v19
	v_max_f32_e32 v34, v18, v18
	v_max_f32_e32 v1, v34, v1
	v_max3_f32 v1, v1, v20, v21
	v_max3_f32 v1, v1, v22, v23
	v_max3_f32 v1, v1, v24, v25
	v_max3_f32 v1, v1, v26, v27
	v_max3_f32 v1, v1, v28, v29
	v_max3_f32 v1, v1, v30, v31
	v_max3_f32 v1, v1, v32, v33
	v_max3_f32 v1, v1, v2, v3
	v_max3_f32 v1, v1, v4, v5
	v_max3_f32 v1, v1, v6, v7
	v_max3_f32 v1, v1, v8, v9
	v_max3_f32 v1, v1, v10, v11
	v_max3_f32 v1, v1, v12, v13
	v_max3_f32 v1, v1, v14, v15
	v_max3_f32 v1, v1, v16, v17
	v_mov_b32_e32 v34, v1
	s_nop 1
	v_permlane32_swap_b32_e32 v1, v34
	v_max_f32_e32 v34, v34, v34
	v_max_f32_e32 v1, v1, v1
	v_max_f32_e32 v1, v1, v34
	v_add_f32_e32 v1, 0xc0a00000, v1
	v_sub_f32_e32 v18, v18, v1
	v_sub_f32_e32 v19, v19, v1
	v_sub_f32_e32 v20, v20, v1
	v_sub_f32_e32 v21, v21, v1
	v_sub_f32_e32 v22, v22, v1
	v_sub_f32_e32 v23, v23, v1
	v_sub_f32_e32 v24, v24, v1
	v_sub_f32_e32 v25, v25, v1
	v_sub_f32_e32 v26, v26, v1
	v_sub_f32_e32 v27, v27, v1
	v_sub_f32_e32 v28, v28, v1
	v_sub_f32_e32 v29, v29, v1
	v_sub_f32_e32 v30, v30, v1
	v_sub_f32_e32 v31, v31, v1
	v_sub_f32_e32 v32, v32, v1
	v_sub_f32_e32 v33, v33, v1
	v_exp_f32_e32 v144, v18
	v_exp_f32_e32 v145, v19
	v_exp_f32_e32 v146, v20
	v_exp_f32_e32 v147, v21
	v_exp_f32_e32 v148, v22
	v_exp_f32_e32 v149, v23
	v_exp_f32_e32 v150, v24
	v_exp_f32_e32 v151, v25
	v_exp_f32_e32 v152, v26
	v_exp_f32_e32 v153, v27
	v_exp_f32_e32 v154, v28
	v_exp_f32_e32 v155, v29
	v_exp_f32_e32 v156, v30
	v_exp_f32_e32 v157, v31
	v_exp_f32_e32 v158, v32
	v_exp_f32_e32 v159, v33
	v_sub_f32_e32 v125, v15, v1
	v_sub_f32_e32 v124, v14, v1
	v_mov_b32_e32 v14, v0
	v_mov_b32_e32 v15, v0
	v_sub_f32_e32 v96, 0x40a00000, v1
	v_sub_f32_e32 v127, v17, v1
	v_sub_f32_e32 v126, v16, v1
	v_sub_f32_e32 v123, v13, v1
	v_sub_f32_e32 v122, v12, v1
	v_sub_f32_e32 v121, v11, v1
	v_sub_f32_e32 v120, v10, v1
	v_sub_f32_e32 v119, v9, v1
	v_sub_f32_e32 v118, v8, v1
	v_sub_f32_e32 v117, v7, v1
	v_sub_f32_e32 v116, v6, v1
	v_sub_f32_e32 v115, v5, v1
	v_sub_f32_e32 v114, v4, v1
	v_sub_f32_e32 v113, v3, v1
	v_sub_f32_e32 v112, v2, v1
	v_mov_b32_e32 v1, v0
	v_mov_b32_e32 v2, v0
	v_mov_b32_e32 v3, v0
	v_mov_b32_e32 v4, v0
	v_mov_b32_e32 v5, v0
	v_mov_b32_e32 v6, v0
	v_mov_b32_e32 v7, v0
	v_mov_b32_e32 v8, v0
	v_mov_b32_e32 v9, v0
	v_mov_b32_e32 v10, v0
	v_mov_b32_e32 v11, v0
	v_mov_b32_e32 v12, v0
	v_mov_b32_e32 v13, v0
	v_mov_b64_e32 v[78:79], v[14:15]
	v_mov_b64_e32 v[62:63], v[14:15]
	v_mov_b64_e32 v[46:47], v[14:15]
	v_mov_b64_e32 v[30:31], v[14:15]
	v_mov_b64_e32 v[94:95], v[14:15]
	v_mov_b32_e32 v97, v96
	v_mov_b32_e32 v98, v96
	v_mov_b32_e32 v99, v96
	v_mov_b32_e32 v100, v96
	v_mov_b32_e32 v101, v96
	v_mov_b32_e32 v102, v96
	v_mov_b32_e32 v103, v96
	v_mov_b32_e32 v104, v96
	v_mov_b32_e32 v105, v96
	v_mov_b32_e32 v106, v96
	v_mov_b32_e32 v107, v96
	v_mov_b32_e32 v108, v96
	v_mov_b32_e32 v109, v96
	v_mov_b32_e32 v110, v96
	v_mov_b32_e32 v111, v96
	v_mov_b64_e32 v[76:77], v[12:13]
	v_mov_b64_e32 v[74:75], v[10:11]
	v_mov_b64_e32 v[72:73], v[8:9]
	v_mov_b64_e32 v[70:71], v[6:7]
	v_mov_b64_e32 v[68:69], v[4:5]
	v_mov_b64_e32 v[66:67], v[2:3]
	v_mov_b64_e32 v[64:65], v[0:1]
	v_mov_b64_e32 v[60:61], v[12:13]
	v_mov_b64_e32 v[58:59], v[10:11]
	v_mov_b64_e32 v[56:57], v[8:9]
	v_mov_b64_e32 v[54:55], v[6:7]
	v_mov_b64_e32 v[52:53], v[4:5]
	v_mov_b64_e32 v[50:51], v[2:3]
	v_mov_b64_e32 v[48:49], v[0:1]
	v_mov_b64_e32 v[44:45], v[12:13]
	v_mov_b64_e32 v[42:43], v[10:11]
	v_mov_b64_e32 v[40:41], v[8:9]
	v_mov_b64_e32 v[38:39], v[6:7]
	v_mov_b64_e32 v[36:37], v[4:5]
	v_mov_b64_e32 v[34:35], v[2:3]
	v_mov_b64_e32 v[32:33], v[0:1]
	v_mov_b64_e32 v[28:29], v[12:13]
	v_mov_b64_e32 v[26:27], v[10:11]
	v_mov_b64_e32 v[24:25], v[8:9]
	v_mov_b64_e32 v[22:23], v[6:7]
	v_mov_b64_e32 v[20:21], v[4:5]
	v_mov_b64_e32 v[18:19], v[2:3]
	v_mov_b64_e32 v[16:17], v[0:1]
	v_mov_b64_e32 v[92:93], v[12:13]
	v_mov_b64_e32 v[90:91], v[10:11]
	v_mov_b64_e32 v[88:89], v[8:9]
	v_mov_b64_e32 v[86:87], v[6:7]
	v_mov_b64_e32 v[84:85], v[4:5]
	v_mov_b64_e32 v[82:83], v[2:3]
	v_mov_b64_e32 v[80:81], v[0:1]
	s_cmp_lg_u32 s92, 0
	s_cbranch_scc1 .LgB_374
	s_branch .LBB0_374
; #define SBAR() __builtin_amdgcn_sched_barrier(0)
; #define DMA(slot, t) do { \
;     __builtin_amdgcn_global_load_lds((const unsigned*)(Kg + (long)(t) * (64 * 256)), (LAS unsigned*)(L3 + K_OFF + (slot) * SHM_T + wid * 1024), 16, 0, 0); \
;     __builtin_amdgcn_global_load_lds((const unsigned*)(Vg + (long)(t) * 8192), (LAS unsigned*)(L3 + (slot) * SHM_T + wid * 1024), 16, 0, 0); } while (0)
; #define BAR() do { asm volatile("s_waitcnt lgkmcnt(0)" ::: "memory"); __builtin_amdgcn_s_barrier(); asm volatile("" ::: "memory"); } while (0)
; #define WAITV(n) asm volatile("s_waitcnt vmcnt(" #n ")" ::: "memory")
; #define RESC(a) do { if (__any((a) < 1.f)) { if (hi == 0) al_l[r32] = (a); asm volatile("s_waitcnt lgkmcnt(0)" ::: "memory"); \
;     for (int r = 0; r < 16; ++r) { const float a_ = al_l[crow(r, hi)]; ls[r] *= a_; for (int d = 0; d < 4; ++d) o[d][r] *= a_; } } } while (0)
; #define QKT(P0, P1, b) qkt(P0, P1, nm, K_lds + (b) * SHM_T, qr, ko, c00, c01, c10, c11)
; #define PIPE1() do { SGB(0x100, 8); SGB(0x400, 4); SGB(0x008, 1); SGB(0x400, 4); SGB(0x008, 1); SGB(0x400, 4); SGB(0x008, 1); SGB(0x400, 4); SGB(0x008, 1); } while (0)
; #define HALF2(Y0, Y1, alY, b) do { PVL(b); const float pm_ = max32(Y0, Y1); adjustSM(Y0, Y1, nm, alY, pm_); SBAR(); \
;     PVM(); exp16(Y0); asm volatile("" : "+v"(Y0)); \
;     SGB(0x008, 1); SGB(0x400, 3); SGB(0x008, 1); SGB(0x400, 3); SGB(0x008, 1); SGB(0x400, 3); SGB(0x008, 1); SGB(0x400, 3); SGB(0x008, 1); SGB(0x400, 4); SBAR(); } while (0)
; __device__ __forceinline__ void body(const unsigned char* Q8b, const unsigned char* K8h, const unsigned char* VT8h, const bf16_t* Gb, bf16_t* Ob, int seq, char* lds, const int wid, ...
;     ...
;   for (int i = 0; i + 2 < NT; i += 2) {
;     SBAR(); QKT(pB0, pB1, (s0 + 1) & 3);
;     finishSM(pA0, pA1, pf); PIPE1(); SBAR();
;     DMA((s0 + 3) & 3, i + 3);
;     SBAR();
;     HALF2(pB0, pB1, alB, s0);
;     WAITV(2);
;     RESC(alB); BAR();
.LBB0_374:
	ds_read_b128 v[2:5], v242 offset:40960
	ds_read_b128 v[6:9], v243 offset:40960
	ds_read_b128 v[128:131], v242 offset:45056
	ds_read_b128 v[132:135], v243 offset:45056
	ds_read_b128 v[194:197], v244 offset:40960
	ds_read_b128 v[198:201], v245 offset:40960
	ds_read_b128 v[246:249], v244 offset:45056
	ds_read_b128 v[250:253], v245 offset:45056
	v_exp_f32_e32 v1, v112
	v_exp_f32_e32 v10, v113
	v_exp_f32_e32 v11, v114
	v_exp_f32_e32 v12, v115
	s_waitcnt lgkmcnt(6)
	s_setprio 1
	v_mfma_scale_f32_32x32x64_f8f6f4 v[160:175], v[2:9], v[176:183], v[96:111], v240, v239 op_sel_hi:[0,0,0]
	v_exp_f32_e32 v6, v116
	v_exp_f32_e32 v7, v117
	v_exp_f32_e32 v8, v118
	v_exp_f32_e32 v9, v119
	v_cvt_pk_fp8_f32 v5, v6, v7
	v_cvt_pk_fp8_f32 v3, v1, v10
	v_cvt_pk_fp8_f32 v5, v8, v9 op_sel:[0,0,1]
	s_waitcnt lgkmcnt(4)
	v_mfma_scale_f32_32x32x64_f8f6f4 v[128:143], v[128:135], v[176:183], v[96:111], v240, v239 op_sel_hi:[0,0,0]
	v_exp_f32_e32 v13, v120
	v_exp_f32_e32 v14, v121
	v_exp_f32_e32 v15, v122
	v_exp_f32_e32 v112, v123
	v_cvt_pk_fp8_f32 v2, v144, v145
	v_cvt_pk_fp8_f32 v4, v148, v149
	v_cvt_pk_fp8_f32 v6, v152, v153
	v_cvt_pk_fp8_f32 v7, v13, v14
	v_cvt_pk_fp8_f32 v8, v156, v157
	v_cvt_pk_fp8_f32 v2, v146, v147 op_sel:[0,0,1]
	v_cvt_pk_fp8_f32 v3, v11, v12 op_sel:[0,0,1]
	v_cvt_pk_fp8_f32 v4, v150, v151 op_sel:[0,0,1]
	v_cvt_pk_fp8_f32 v6, v154, v155 op_sel:[0,0,1]
	v_cvt_pk_fp8_f32 v7, v15, v112 op_sel:[0,0,1]
	v_cvt_pk_fp8_f32 v8, v158, v159 op_sel:[0,0,1]
	s_waitcnt lgkmcnt(2)
	v_mfma_scale_f32_32x32x64_f8f6f4 v[160:175], v[194:201], v[184:191], v[160:175], v240, v239 op_sel_hi:[0,0,0]
	v_exp_f32_e32 v113, v124
	v_exp_f32_e32 v114, v125
	v_exp_f32_e32 v1, v126
	v_exp_f32_e32 v10, v127
	v_cvt_pk_fp8_f32 v9, v113, v114
	s_waitcnt lgkmcnt(0)
	v_cvt_pk_fp8_f32 v9, v1, v10 op_sel:[0,0,1]
	v_mfma_scale_f32_32x32x64_f8f6f4 v[128:143], v[246:253], v[184:191], v[128:143], v240, v239 op_sel_hi:[0,0,0]
	s_setprio 0
	s_add_i32 m0, s68, 0xe000
	s_nop 0
	global_load_lds_dwordx4 v192, s[98:99]
	s_add_i32 m0, s68, 0x6000
	s_nop 0
	global_load_lds_dwordx4 v193, s[100:101]
	ds_read_b128 v[194:197], v254
	ds_read_b128 v[148:151], v254 offset:2048
	ds_read_b128 v[198:201], v255
	ds_read_b128 v[152:155], v255 offset:2048
	ds_read_b128 v[120:123], v254 offset:4096
	ds_read_b128 v[112:115], v254 offset:6144
	ds_read_b128 v[124:127], v255 offset:4096
	ds_read_b128 v[116:119], v255 offset:6144
	v_max_f32_e32 v1, v160, v161
	v_max3_f32 v1, v1, v162, v163
	v_max3_f32 v1, v1, v164, v165
	v_max3_f32 v1, v1, v166, v167
	v_max3_f32 v1, v1, v168, v169
	v_max3_f32 v1, v1, v170, v171
	v_max3_f32 v1, v1, v172, v173
	v_max3_f32 v1, v1, v174, v175
	v_max3_f32 v1, v1, v128, v129
	v_max3_f32 v1, v1, v130, v131
	v_max3_f32 v1, v1, v132, v133
	v_max3_f32 v1, v1, v134, v135
	v_max3_f32 v1, v1, v136, v137
	v_max3_f32 v1, v1, v138, v139
	v_max3_f32 v1, v1, v140, v141
	v_max3_f32 v1, v1, v142, v143
	v_cmp_lt_f32_e32 vcc, s80, v1
	s_cbranch_vccnz .LBB0_383
.LBB0_375:
	s_waitcnt lgkmcnt(0)
	v_mfma_scale_f32_32x32x64_f8f6f4 v[64:79], v[2:9], v[194:201], v[64:79], v240, v240 op_sel_hi:[0,0,0]
	v_exp_f32_e32 v144, v160
	v_exp_f32_e32 v145, v161
	v_exp_f32_e32 v146, v162
	v_mfma_scale_f32_32x32x64_f8f6f4 v[48:63], v[2:9], v[148:155], v[48:63], v240, v240 op_sel_hi:[0,0,0]
	v_exp_f32_e32 v147, v163
	v_exp_f32_e32 v148, v164
	v_exp_f32_e32 v149, v165
	v_mfma_scale_f32_32x32x64_f8f6f4 v[32:47], v[2:9], v[120:127], v[32:47], v240, v240 op_sel_hi:[0,0,0]
	v_exp_f32_e32 v150, v166
	v_exp_f32_e32 v151, v167
	v_exp_f32_e32 v152, v168
	v_mfma_scale_f32_32x32x64_f8f6f4 v[16:31], v[2:9], v[112:119], v[16:31], v240, v240 op_sel_hi:[0,0,0]
	v_exp_f32_e32 v153, v169
	v_exp_f32_e32 v154, v170
	v_exp_f32_e32 v155, v171
	v_mfma_scale_f32_32x32x64_f8f6f4 v[80:95], v[2:9], v[228:235], v[80:95], v240, v240 op_sel_hi:[0,0,0]
	v_exp_f32_e32 v156, v172
	v_exp_f32_e32 v157, v173
	v_exp_f32_e32 v158, v174
	v_exp_f32_e32 v159, v175
	s_waitcnt vmcnt(2)
	s_cmp_lg_u32 s93, 0
	s_cbranch_scc1 .Lr1_LBB0

; #define SBAR() __builtin_amdgcn_sched_barrier(0)
; #define DMA(slot, t) do { \
;     __builtin_amdgcn_global_load_lds((const unsigned*)(Kg + (long)(t) * (64 * 256)), (LAS unsigned*)(L3 + K_OFF + (slot) * SHM_T + wid * 1024), 16, 0, 0); \
;     __builtin_amdgcn_global_load_lds((const unsigned*)(Vg + (long)(t) * 8192), (LAS unsigned*)(L3 + (slot) * SHM_T + wid * 1024), 16, 0, 0); } while (0)
; #define BAR() do { asm volatile("s_waitcnt lgkmcnt(0)" ::: "memory"); __builtin_amdgcn_s_barrier(); asm volatile("" ::: "memory"); } while (0)
; #define WAITV(n) asm volatile("s_waitcnt vmcnt(" #n ")" ::: "memory")
; #define RESC(a) do { if (__any((a) < 1.f)) { if (hi == 0) al_l[r32] = (a); asm volatile("s_waitcnt lgkmcnt(0)" ::: "memory"); \
;     for (int r = 0; r < 16; ++r) { const float a_ = al_l[crow(r, hi)]; ls[r] *= a_; for (int d = 0; d < 4; ++d) o[d][r] *= a_; } } } while (0)
; #define QKT(P0, P1, b) qkt(P0, P1, nm, K_lds + (b) * SHM_T, qr, ko, c00, c01, c10, c11)
; #define PIPE1() do { SGB(0x100, 8); SGB(0x400, 4); SGB(0x008, 1); SGB(0x400, 4); SGB(0x008, 1); SGB(0x400, 4); SGB(0x008, 1); SGB(0x400, 4); SGB(0x008, 1); } while (0)
; #define HALF2(Y0, Y1, alY, b) do { PVL(b); const float pm_ = max32(Y0, Y1); adjustSM(Y0, Y1, nm, alY, pm_); SBAR(); \
;     PVM(); exp16(Y0); asm volatile("" : "+v"(Y0)); \
;     SGB(0x008, 1); SGB(0x400, 3); SGB(0x008, 1); SGB(0x400, 3); SGB(0x008, 1); SGB(0x400, 3); SGB(0x008, 1); SGB(0x400, 3); SGB(0x008, 1); SGB(0x400, 4); SBAR(); } while (0)
; __device__ __forceinline__ void body(const unsigned char* Q8b, const unsigned char* K8h, const unsigned char* VT8h, const bf16_t* Gb, bf16_t* Ob, int seq, char* lds, const int wid, ...
;     ...
;   for (int i = 0; i + 2 < NT; i += 2) {
;     SBAR(); QKT(pB0, pB1, (s0 + 1) & 3);
;     finishSM(pA0, pA1, pf); PIPE1(); SBAR();
;     DMA((s0 + 3) & 3, i + 3);
;     SBAR();
;     HALF2(pB0, pB1, alB, s0);
;     ...
;     SBAR(); QKT(pA0, pA1, (s0 + 2) & 3);
;     finishSM(pB0, pB1, pf); PIPE1(); SBAR();
;     { const int t4 = (i + 4 < NT) ? i + 4 : NT - 1; DMA(s0, t4); }
;     SBAR();
;     HALF2(pA0, pA1, alA, (s0 + 1) & 3);
;     WAITV(2);
;     RESC(alA); BAR();
;     s0 = (s0 + 2) & 3;
;   }
.LBB0_380:
	s_waitcnt lgkmcnt(0)
	v_mfma_scale_f32_32x32x64_f8f6f4 v[64:79], v[2:9], v[194:201], v[64:79], v240, v240 op_sel_hi:[0,0,0]
	v_exp_f32_e32 v144, v160
	v_exp_f32_e32 v145, v161
	v_exp_f32_e32 v146, v162
	v_mfma_scale_f32_32x32x64_f8f6f4 v[48:63], v[2:9], v[148:155], v[48:63], v240, v240 op_sel_hi:[0,0,0]
	v_exp_f32_e32 v147, v163
	v_exp_f32_e32 v148, v164
	v_exp_f32_e32 v149, v165
	v_mfma_scale_f32_32x32x64_f8f6f4 v[32:47], v[2:9], v[136:143], v[32:47], v240, v240 op_sel_hi:[0,0,0]
	v_exp_f32_e32 v150, v166
	v_exp_f32_e32 v151, v167
	v_exp_f32_e32 v152, v168
	v_mfma_scale_f32_32x32x64_f8f6f4 v[16:31], v[2:9], v[128:135], v[16:31], v240, v240 op_sel_hi:[0,0,0]
	v_exp_f32_e32 v153, v169
	v_exp_f32_e32 v154, v170
	v_exp_f32_e32 v155, v171
	v_mfma_scale_f32_32x32x64_f8f6f4 v[80:95], v[2:9], v[228:235], v[80:95], v240, v240 op_sel_hi:[0,0,0]
	v_exp_f32_e32 v156, v172
	v_exp_f32_e32 v157, v173
	v_exp_f32_e32 v158, v174
	v_exp_f32_e32 v159, v175
	s_waitcnt vmcnt(2)
	s_cmp_lg_u32 s93, 0
	s_cbranch_scc1 .Lr2_LBB0
.LBB0_373:
	s_waitcnt lgkmcnt(0)
	s_barrier
	s_add_i32 s45, s45, 2
	s_add_u32 s100, s100, 0x4000
	s_addc_u32 s101, s101, 0
	s_add_u32 s98, s98, 0x8000
	s_addc_u32 s99, s99, 0
	s_cmpk_gt_u32 s45, 0x7d
	s_cbranch_scc1 .LBB0_385
.Lc2_374:
	ds_read_b128 v[2:5], v242 offset:57344
	ds_read_b128 v[6:9], v243 offset:57344
	ds_read_b128 v[128:131], v242 offset:61440
	ds_read_b128 v[132:135], v243 offset:61440
	ds_read_b128 v[194:197], v244 offset:57344
	ds_read_b128 v[198:201], v245 offset:57344
	ds_read_b128 v[246:249], v244 offset:61440
	ds_read_b128 v[250:253], v245 offset:61440
	v_exp_f32_e32 v1, v112
	v_exp_f32_e32 v10, v113
	v_exp_f32_e32 v11, v114
	v_exp_f32_e32 v12, v115
	s_waitcnt lgkmcnt(6)
	s_setprio 1
	v_mfma_scale_f32_32x32x64_f8f6f4 v[160:175], v[2:9], v[176:183], v[96:111], v240, v239 op_sel_hi:[0,0,0]
	v_exp_f32_e32 v6, v116
	v_exp_f32_e32 v7, v117
	v_exp_f32_e32 v8, v118
	v_exp_f32_e32 v9, v119
	v_cvt_pk_fp8_f32 v5, v6, v7
	v_cvt_pk_fp8_f32 v3, v1, v10
	v_cvt_pk_fp8_f32 v5, v8, v9 op_sel:[0,0,1]
	s_waitcnt lgkmcnt(4)
	v_mfma_scale_f32_32x32x64_f8f6f4 v[128:143], v[128:135], v[176:183], v[96:111], v240, v239 op_sel_hi:[0,0,0]
	v_exp_f32_e32 v13, v120
	v_exp_f32_e32 v14, v121
	v_exp_f32_e32 v15, v122
	v_exp_f32_e32 v112, v123
	v_cvt_pk_fp8_f32 v2, v144, v145
	v_cvt_pk_fp8_f32 v4, v148, v149
	v_cvt_pk_fp8_f32 v6, v152, v153
	v_cvt_pk_fp8_f32 v7, v13, v14
	v_cvt_pk_fp8_f32 v8, v156, v157
	v_cvt_pk_fp8_f32 v2, v146, v147 op_sel:[0,0,1]
	v_cvt_pk_fp8_f32 v3, v11, v12 op_sel:[0,0,1]
	v_cvt_pk_fp8_f32 v4, v150, v151 op_sel:[0,0,1]
	v_cvt_pk_fp8_f32 v6, v154, v155 op_sel:[0,0,1]
	v_cvt_pk_fp8_f32 v7, v15, v112 op_sel:[0,0,1]
	v_cvt_pk_fp8_f32 v8, v158, v159 op_sel:[0,0,1]
	s_waitcnt lgkmcnt(2)
	v_mfma_scale_f32_32x32x64_f8f6f4 v[160:175], v[194:201], v[184:191], v[160:175], v240, v239 op_sel_hi:[0,0,0]
	v_exp_f32_e32 v113, v124
	v_exp_f32_e32 v114, v125
	v_exp_f32_e32 v1, v126
	v_exp_f32_e32 v10, v127
	v_cvt_pk_fp8_f32 v9, v113, v114
	s_waitcnt lgkmcnt(0)
	v_cvt_pk_fp8_f32 v9, v1, v10 op_sel:[0,0,1]
	v_mfma_scale_f32_32x32x64_f8f6f4 v[128:143], v[246:253], v[184:191], v[128:143], v240, v239 op_sel_hi:[0,0,0]
	s_setprio 0
	s_add_i32 m0, s68, 0xa000
	s_nop 0
	global_load_lds_dwordx4 v192, s[98:99]
	s_add_i32 m0, s68, 0x2000
	s_nop 0
	global_load_lds_dwordx4 v193, s[100:101]
	ds_read_b128 v[194:197], v254 offset:16384
	ds_read_b128 v[148:151], v254 offset:18432
	ds_read_b128 v[198:201], v255 offset:16384
	ds_read_b128 v[152:155], v255 offset:18432
	ds_read_b128 v[120:123], v254 offset:20480
	ds_read_b128 v[112:115], v254 offset:22528
	ds_read_b128 v[124:127], v255 offset:20480
	ds_read_b128 v[116:119], v255 offset:22528
	v_max_f32_e32 v1, v160, v161
	v_max3_f32 v1, v1, v162, v163
	v_max3_f32 v1, v1, v164, v165
	v_max3_f32 v1, v1, v166, v167
	v_max3_f32 v1, v1, v168, v169
	v_max3_f32 v1, v1, v170, v171
	v_max3_f32 v1, v1, v172, v173
	v_max3_f32 v1, v1, v174, v175
	v_max3_f32 v1, v1, v128, v129
	v_max3_f32 v1, v1, v130, v131
	v_max3_f32 v1, v1, v132, v133
	v_max3_f32 v1, v1, v134, v135
	v_max3_f32 v1, v1, v136, v137
	v_max3_f32 v1, v1, v138, v139
	v_max3_f32 v1, v1, v140, v141
	v_max3_f32 v1, v1, v142, v143
	v_cmp_lt_f32_e32 vcc, s80, v1
	s_cbranch_vccnz .Lc2_383

.Lr1_LBB0:
	s_mov_b32 s93, 0
	s_and_saveexec_b64 s[56:57], s[4:5]
	ds_write_b32 v236, v1 offset:128
	s_or_b64 exec, exec, s[56:57]
	s_waitcnt lgkmcnt(0)
	v_add_u32_e32 v1, s67, v237
	ds_read_b128 v[2:5], v1 offset:224
	ds_read_b128 v[6:9], v1 offset:192
	ds_read_b128 v[10:13], v1 offset:160
	ds_read_b128 v[112:115], v1 offset:128
	s_waitcnt lgkmcnt(0)
	v_pk_mul_f32 v[76:77], v[76:77], v[2:3]
	v_pk_mul_f32 v[72:73], v[72:73], v[6:7]
	v_pk_mul_f32 v[68:69], v[68:69], v[10:11]
	v_pk_mul_f32 v[78:79], v[78:79], v[4:5]
	v_pk_mul_f32 v[74:75], v[74:75], v[8:9]
	v_pk_mul_f32 v[70:71], v[70:71], v[12:13]
	v_pk_mul_f32 v[66:67], v[66:67], v[114:115]
	v_pk_mul_f32 v[64:65], v[64:65], v[112:113]
	v_pk_mul_f32 v[60:61], v[60:61], v[2:3]
	v_pk_mul_f32 v[56:57], v[56:57], v[6:7]
	v_pk_mul_f32 v[52:53], v[52:53], v[10:11]
	v_pk_mul_f32 v[62:63], v[62:63], v[4:5]
	v_pk_mul_f32 v[58:59], v[58:59], v[8:9]
	v_pk_mul_f32 v[54:55], v[54:55], v[12:13]
	v_pk_mul_f32 v[50:51], v[50:51], v[114:115]
	v_pk_mul_f32 v[48:49], v[48:49], v[112:113]
	v_pk_mul_f32 v[44:45], v[44:45], v[2:3]
	v_pk_mul_f32 v[40:41], v[40:41], v[6:7]
	v_pk_mul_f32 v[36:37], v[36:37], v[10:11]
	v_pk_mul_f32 v[46:47], v[46:47], v[4:5]
	v_pk_mul_f32 v[42:43], v[42:43], v[8:9]
	v_pk_mul_f32 v[38:39], v[38:39], v[12:13]
	v_pk_mul_f32 v[34:35], v[34:35], v[114:115]
	v_pk_mul_f32 v[32:33], v[32:33], v[112:113]
	v_pk_mul_f32 v[28:29], v[28:29], v[2:3]
	v_pk_mul_f32 v[24:25], v[24:25], v[6:7]
	v_pk_mul_f32 v[20:21], v[20:21], v[10:11]
	v_pk_mul_f32 v[30:31], v[30:31], v[4:5]
	v_pk_mul_f32 v[26:27], v[26:27], v[8:9]
	v_pk_mul_f32 v[22:23], v[22:23], v[12:13]
	v_pk_mul_f32 v[18:19], v[18:19], v[114:115]
	v_pk_mul_f32 v[16:17], v[16:17], v[112:113]
	v_pk_mul_f32 v[92:93], v[92:93], v[2:3]
	v_pk_mul_f32 v[88:89], v[88:89], v[6:7]
	v_pk_mul_f32 v[84:85], v[84:85], v[10:11]
	v_pk_mul_f32 v[94:95], v[94:95], v[4:5]
	v_pk_mul_f32 v[90:91], v[90:91], v[8:9]
	v_pk_mul_f32 v[86:87], v[86:87], v[12:13]
	v_pk_mul_f32 v[82:83], v[82:83], v[114:115]
	v_pk_mul_f32 v[80:81], v[80:81], v[112:113]
	s_branch .LBB0_379
.Lr2_LBB0:
	s_mov_b32 s93, 0
	s_and_saveexec_b64 s[56:57], s[4:5]
	s_cbranch_execz .LBB0_372
	ds_write_b32 v236, v1 offset:128
	s_branch .LBB0_372
.LBB0_372:
	s_or_b64 exec, exec, s[56:57]
	s_waitcnt lgkmcnt(0)
	v_add_u32_e32 v1, s67, v237
	ds_read_b128 v[2:5], v1 offset:224
	ds_read_b128 v[6:9], v1 offset:192
	ds_read_b128 v[10:13], v1 offset:160
	ds_read_b128 v[128:131], v1 offset:128
	s_waitcnt lgkmcnt(0)
	v_pk_mul_f32 v[76:77], v[76:77], v[2:3]
	v_pk_mul_f32 v[72:73], v[72:73], v[6:7]
	v_pk_mul_f32 v[68:69], v[68:69], v[10:11]
	v_pk_mul_f32 v[78:79], v[78:79], v[4:5]
	v_pk_mul_f32 v[74:75], v[74:75], v[8:9]
	v_pk_mul_f32 v[70:71], v[70:71], v[12:13]
	v_pk_mul_f32 v[66:67], v[66:67], v[130:131]
	v_pk_mul_f32 v[64:65], v[64:65], v[128:129]
	v_pk_mul_f32 v[60:61], v[60:61], v[2:3]
	v_pk_mul_f32 v[56:57], v[56:57], v[6:7]
	v_pk_mul_f32 v[52:53], v[52:53], v[10:11]
	v_pk_mul_f32 v[62:63], v[62:63], v[4:5]
	v_pk_mul_f32 v[58:59], v[58:59], v[8:9]
	v_pk_mul_f32 v[54:55], v[54:55], v[12:13]
	v_pk_mul_f32 v[50:51], v[50:51], v[130:131]
	v_pk_mul_f32 v[48:49], v[48:49], v[128:129]
	v_pk_mul_f32 v[44:45], v[44:45], v[2:3]
	v_pk_mul_f32 v[40:41], v[40:41], v[6:7]
	v_pk_mul_f32 v[36:37], v[36:37], v[10:11]
	v_pk_mul_f32 v[46:47], v[46:47], v[4:5]
	v_pk_mul_f32 v[42:43], v[42:43], v[8:9]
	v_pk_mul_f32 v[38:39], v[38:39], v[12:13]
	v_pk_mul_f32 v[34:35], v[34:35], v[130:131]
	v_pk_mul_f32 v[32:33], v[32:33], v[128:129]
	v_pk_mul_f32 v[28:29], v[28:29], v[2:3]
	v_pk_mul_f32 v[24:25], v[24:25], v[6:7]
	v_pk_mul_f32 v[20:21], v[20:21], v[10:11]
	v_pk_mul_f32 v[30:31], v[30:31], v[4:5]
	v_pk_mul_f32 v[26:27], v[26:27], v[8:9]
	v_pk_mul_f32 v[22:23], v[22:23], v[12:13]
	v_pk_mul_f32 v[18:19], v[18:19], v[130:131]
	v_pk_mul_f32 v[16:17], v[16:17], v[128:129]
	v_pk_mul_f32 v[92:93], v[92:93], v[2:3]
	v_pk_mul_f32 v[88:89], v[88:89], v[6:7]
	v_pk_mul_f32 v[84:85], v[84:85], v[10:11]
	v_pk_mul_f32 v[94:95], v[94:95], v[4:5]
	v_pk_mul_f32 v[90:91], v[90:91], v[8:9]
	v_pk_mul_f32 v[86:87], v[86:87], v[12:13]
	v_pk_mul_f32 v[82:83], v[82:83], v[130:131]
	v_pk_mul_f32 v[80:81], v[80:81], v[128:129]
	s_branch .LBB0_373

; #define SBAR() __builtin_amdgcn_sched_barrier(0)
; #define DMA(slot, t) do { \
;     __builtin_amdgcn_global_load_lds((const unsigned*)(Kg + (long)(t) * (64 * 256)), (LAS unsigned*)(L3 + K_OFF + (slot) * SHM_T + wid * 1024), 16, 0, 0); \
;     __builtin_amdgcn_global_load_lds((const unsigned*)(Vg + (long)(t) * 8192), (LAS unsigned*)(L3 + (slot) * SHM_T + wid * 1024), 16, 0, 0); } while (0)
; #define BAR() do { asm volatile("s_waitcnt lgkmcnt(0)" ::: "memory"); __builtin_amdgcn_s_barrier(); asm volatile("" ::: "memory"); } while (0)
; #define WAITV(n) asm volatile("s_waitcnt vmcnt(" #n ")" ::: "memory")
; #define RESC(a) do { if (__any((a) < 1.f)) { if (hi == 0) al_l[r32] = (a); asm volatile("s_waitcnt lgkmcnt(0)" ::: "memory"); \
;     for (int r = 0; r < 16; ++r) { const float a_ = al_l[crow(r, hi)]; ls[r] *= a_; for (int d = 0; d < 4; ++d) o[d][r] *= a_; } } } while (0)
; #define QKT(P0, P1, b) qkt(P0, P1, nm, K_lds + (b) * SHM_T, qr, ko, c00, c01, c10, c11)
; #define PIPE1() do { SGB(0x100, 8); SGB(0x400, 4); SGB(0x008, 1); SGB(0x400, 4); SGB(0x008, 1); SGB(0x400, 4); SGB(0x008, 1); SGB(0x400, 4); SGB(0x008, 1); } while (0)
; #define HALF2(Y0, Y1, alY, b) do { PVL(b); const float pm_ = max32(Y0, Y1); adjustSM(Y0, Y1, nm, alY, pm_); SBAR(); \
;     PVM(); exp16(Y0); asm volatile("" : "+v"(Y0)); \
;     SGB(0x008, 1); SGB(0x400, 3); SGB(0x008, 1); SGB(0x400, 3); SGB(0x008, 1); SGB(0x400, 3); SGB(0x008, 1); SGB(0x400, 3); SGB(0x008, 1); SGB(0x400, 4); SBAR(); } while (0)
; __device__ __forceinline__ void adjustSM(f32x16& p0, f32x16& p1, f32x16& nm, float& alpha, const float pmax) {
;   alpha = 1.f;
;   if (__builtin_expect(__any(pmax > PSHIFT + THR2), 0)) {
;     const float delta = (pmax > PSHIFT + THR2) ? (pmax - PSHIFT) : 0.f;
;     alpha = __builtin_amdgcn_exp2f(-delta);
;     for (int r = 0; r < 16; ++r) { p0[r] -= delta; p1[r] -= delta; nm[r] -= delta; }
;   }
; }
; __device__ __forceinline__ void body(const unsigned char* Q8b, const unsigned char* K8h, const unsigned char* VT8h, const bf16_t* Gb, bf16_t* Ob, int seq, char* lds, const int wid, ...
;     ...
;   for (int i = 0; i + 2 < NT; i += 2) {
;     SBAR(); QKT(pB0, pB1, (s0 + 1) & 3);
;     finishSM(pA0, pA1, pf); PIPE1(); SBAR();
;     DMA((s0 + 3) & 3, i + 3);
;     SBAR();
;     HALF2(pB0, pB1, alB, s0);
;     WAITV(2);
;     RESC(alB); BAR();
.Lc2_384:
	v_mov_b32_e32 v10, v1
	s_nop 1
	v_permlane32_swap_b32_e32 v1, v10
	v_max_f32_e32 v10, v1, v10
	v_cmp_lt_f32_e32 vcc, s80, v10
	s_mov_b32 s93, 1
	v_add_f32_e32 v1, 0xc0a00000, v10
	s_nop 0
	v_cndmask_b32_e32 v10, 0, v1, vcc
	v_exp_f32_e64 v1, -v10
	v_pk_add_f32 v[160:161], v[160:161], v[10:11] op_sel_hi:[1,0] neg_lo:[0,1] neg_hi:[0,1]
	v_pk_add_f32 v[162:163], v[162:163], v[10:11] op_sel_hi:[1,0] neg_lo:[0,1] neg_hi:[0,1]
	v_pk_add_f32 v[164:165], v[164:165], v[10:11] op_sel_hi:[1,0] neg_lo:[0,1] neg_hi:[0,1]
	v_pk_add_f32 v[166:167], v[166:167], v[10:11] op_sel_hi:[1,0] neg_lo:[0,1] neg_hi:[0,1]
	v_pk_add_f32 v[168:169], v[168:169], v[10:11] op_sel_hi:[1,0] neg_lo:[0,1] neg_hi:[0,1]
	v_pk_add_f32 v[170:171], v[170:171], v[10:11] op_sel_hi:[1,0] neg_lo:[0,1] neg_hi:[0,1]
	v_pk_add_f32 v[172:173], v[172:173], v[10:11] op_sel_hi:[1,0] neg_lo:[0,1] neg_hi:[0,1]
	v_pk_add_f32 v[174:175], v[174:175], v[10:11] op_sel_hi:[1,0] neg_lo:[0,1] neg_hi:[0,1]
	v_sub_f32_e32 v127, v127, v10
	v_sub_f32_e32 v126, v126, v10
	v_sub_f32_e32 v125, v125, v10
	v_sub_f32_e32 v124, v124, v10
	v_sub_f32_e32 v123, v123, v10
	v_sub_f32_e32 v122, v122, v10
	v_sub_f32_e32 v121, v121, v10
	v_sub_f32_e32 v120, v120, v10
	v_sub_f32_e32 v119, v119, v10
	v_sub_f32_e32 v118, v118, v10
	v_sub_f32_e32 v117, v117, v10
	v_sub_f32_e32 v116, v116, v10
	v_sub_f32_e32 v115, v115, v10
	v_sub_f32_e32 v114, v114, v10
	v_sub_f32_e32 v113, v113, v10
	v_sub_f32_e32 v112, v112, v10
	v_sub_f32_e32 v111, v111, v10
	v_sub_f32_e32 v110, v110, v10
	v_sub_f32_e32 v109, v109, v10
	v_sub_f32_e32 v108, v108, v10
	v_sub_f32_e32 v107, v107, v10
	v_sub_f32_e32 v106, v106, v10
	v_sub_f32_e32 v105, v105, v10
	v_sub_f32_e32 v104, v104, v10
	v_sub_f32_e32 v103, v103, v10
	v_sub_f32_e32 v102, v102, v10
	v_sub_f32_e32 v101, v101, v10
	v_sub_f32_e32 v100, v100, v10
	v_sub_f32_e32 v99, v99, v10
	v_sub_f32_e32 v98, v98, v10
	v_sub_f32_e32 v97, v97, v10
	v_sub_f32_e32 v96, v96, v10
	s_branch .Lc2_380
.LgB_374:
	ds_read_b128 v[2:5], v242 offset:40960
	ds_read_b128 v[6:9], v243 offset:40960
	ds_read_b128 v[128:131], v242 offset:45056
	ds_read_b128 v[132:135], v243 offset:45056
	ds_read_b128 v[194:197], v244 offset:40960
	ds_read_b128 v[198:201], v245 offset:40960
	ds_read_b128 v[246:249], v244 offset:45056
	ds_read_b128 v[250:253], v245 offset:45056
	v_exp_f32_e32 v1, v112
	v_exp_f32_e32 v10, v113
	v_exp_f32_e32 v11, v114
	v_exp_f32_e32 v12, v115
	s_waitcnt lgkmcnt(6)
	s_setprio 1
	v_mfma_scale_f32_32x32x64_f8f6f4 v[160:175], v[2:9], v[176:183], v[96:111], v240, v239 op_sel_hi:[0,0,0]
	v_exp_f32_e32 v6, v116
	v_exp_f32_e32 v7, v117
	v_exp_f32_e32 v8, v118
	v_exp_f32_e32 v9, v119
	v_cvt_pk_fp8_f32 v5, v6, v7
	v_cvt_pk_fp8_f32 v3, v1, v10
	v_cvt_pk_fp8_f32 v5, v8, v9 op_sel:[0,0,1]
	s_waitcnt lgkmcnt(4)
	v_mfma_scale_f32_32x32x64_f8f6f4 v[128:143], v[128:135], v[176:183], v[96:111], v240, v239 op_sel_hi:[0,0,0]
	v_exp_f32_e32 v13, v120
	v_exp_f32_e32 v14, v121
	v_exp_f32_e32 v15, v122
	v_exp_f32_e32 v112, v123
	v_cvt_pk_fp8_f32 v2, v144, v145
	v_cvt_pk_fp8_f32 v4, v148, v149
	v_cvt_pk_fp8_f32 v6, v152, v153
	v_cvt_pk_fp8_f32 v7, v13, v14
	v_cvt_pk_fp8_f32 v8, v156, v157
	v_cvt_pk_fp8_f32 v2, v146, v147 op_sel:[0,0,1]
	v_cvt_pk_fp8_f32 v3, v11, v12 op_sel:[0,0,1]
	v_cvt_pk_fp8_f32 v4, v150, v151 op_sel:[0,0,1]
	v_cvt_pk_fp8_f32 v6, v154, v155 op_sel:[0,0,1]
	v_cvt_pk_fp8_f32 v7, v15, v112 op_sel:[0,0,1]
	v_cvt_pk_fp8_f32 v8, v158, v159 op_sel:[0,0,1]
	s_waitcnt lgkmcnt(2)
	v_mfma_scale_f32_32x32x64_f8f6f4 v[160:175], v[194:201], v[184:191], v[160:175], v240, v239 op_sel_hi:[0,0,0]
	v_exp_f32_e32 v113, v124
	v_exp_f32_e32 v114, v125
	v_exp_f32_e32 v1, v126
	v_exp_f32_e32 v10, v127
	v_cvt_pk_fp8_f32 v9, v113, v114
	s_waitcnt lgkmcnt(0)
	v_cvt_pk_fp8_f32 v9, v1, v10 op_sel:[0,0,1]
	v_mfma_scale_f32_32x32x64_f8f6f4 v[128:143], v[246:253], v[184:191], v[128:143], v240, v239 op_sel_hi:[0,0,0]
	s_setprio 0
	s_add_i32 m0, s68, 0xe000
	s_nop 0
	global_load_lds_dwordx4 v192, s[98:99]
	s_add_i32 m0, s68, 0x6000
	s_nop 0
	global_load_lds_dwordx4 v193, s[100:101]
	ds_read_b128 v[194:197], v254
	ds_read_b128 v[148:151], v254 offset:2048
	ds_read_b128 v[198:201], v255
	ds_read_b128 v[152:155], v255 offset:2048
	ds_read_b128 v[120:123], v254 offset:4096
	ds_read_b128 v[112:115], v254 offset:6144
	ds_read_b128 v[124:127], v255 offset:4096
	ds_read_b128 v[116:119], v255 offset:6144
	v_max_f32_e32 v1, v160, v161
	v_max3_f32 v1, v1, v162, v163
	v_max3_f32 v1, v1, v164, v165
	v_max3_f32 v1, v1, v166, v167
	v_max3_f32 v1, v1, v168, v169
	v_max3_f32 v1, v1, v170, v171
	v_max3_f32 v1, v1, v172, v173
	v_max3_f32 v1, v1, v174, v175
	v_max3_f32 v1, v1, v128, v129
	v_max3_f32 v1, v1, v130, v131
	v_max3_f32 v1, v1, v132, v133
	v_max3_f32 v1, v1, v134, v135
	v_max3_f32 v1, v1, v136, v137
	v_max3_f32 v1, v1, v138, v139
	v_max3_f32 v1, v1, v140, v141
	v_max3_f32 v1, v1, v142, v143
	v_cmp_lt_f32_e32 vcc, s80, v1
	s_cbranch_vccnz .LgB_383
.LgB_375:
	s_waitcnt vmcnt(2) lgkmcnt(0)
	s_barrier
	v_mfma_scale_f32_32x32x64_f8f6f4 v[64:79], v[2:9], v[194:201], v[64:79], v240, v240 op_sel_hi:[0,0,0]
	v_exp_f32_e32 v144, v160
	v_exp_f32_e32 v145, v161
	v_exp_f32_e32 v146, v162
	v_mfma_scale_f32_32x32x64_f8f6f4 v[48:63], v[2:9], v[148:155], v[48:63], v240, v240 op_sel_hi:[0,0,0]
	v_exp_f32_e32 v147, v163
	v_exp_f32_e32 v148, v164
	v_exp_f32_e32 v149, v165
	v_mfma_scale_f32_32x32x64_f8f6f4 v[32:47], v[2:9], v[120:127], v[32:47], v240, v240 op_sel_hi:[0,0,0]
	v_exp_f32_e32 v150, v166
	v_exp_f32_e32 v151, v167
	v_exp_f32_e32 v152, v168
	v_mfma_scale_f32_32x32x64_f8f6f4 v[16:31], v[2:9], v[112:119], v[16:31], v240, v240 op_sel_hi:[0,0,0]
	v_exp_f32_e32 v153, v169
	v_exp_f32_e32 v154, v170
	v_exp_f32_e32 v155, v171
	v_mfma_scale_f32_32x32x64_f8f6f4 v[80:95], v[2:9], v[228:235], v[80:95], v240, v240 op_sel_hi:[0,0,0]
	v_exp_f32_e32 v156, v172
	v_exp_f32_e32 v157, v173
	v_exp_f32_e32 v158, v174
	v_exp_f32_e32 v159, v175
	s_cmp_lg_u32 s93, 0
	s_cbranch_scc1 .Lr1_LgB

; #define SBAR() __builtin_amdgcn_sched_barrier(0)
; #define DMA(slot, t) do { \
;     __builtin_amdgcn_global_load_lds((const unsigned*)(Kg + (long)(t) * (64 * 256)), (LAS unsigned*)(L3 + K_OFF + (slot) * SHM_T + wid * 1024), 16, 0, 0); \
;     __builtin_amdgcn_global_load_lds((const unsigned*)(Vg + (long)(t) * 8192), (LAS unsigned*)(L3 + (slot) * SHM_T + wid * 1024), 16, 0, 0); } while (0)
; #define BAR() do { asm volatile("s_waitcnt lgkmcnt(0)" ::: "memory"); __builtin_amdgcn_s_barrier(); asm volatile("" ::: "memory"); } while (0)
; #define WAITV(n) asm volatile("s_waitcnt vmcnt(" #n ")" ::: "memory")
; #define RESC(a) do { if (__any((a) < 1.f)) { if (hi == 0) al_l[r32] = (a); asm volatile("s_waitcnt lgkmcnt(0)" ::: "memory"); \
;     for (int r = 0; r < 16; ++r) { const float a_ = al_l[crow(r, hi)]; ls[r] *= a_; for (int d = 0; d < 4; ++d) o[d][r] *= a_; } } } while (0)
; #define QKT(P0, P1, b) qkt(P0, P1, nm, K_lds + (b) * SHM_T, qr, ko, c00, c01, c10, c11)
; #define PIPE1() do { SGB(0x100, 8); SGB(0x400, 4); SGB(0x008, 1); SGB(0x400, 4); SGB(0x008, 1); SGB(0x400, 4); SGB(0x008, 1); SGB(0x400, 4); SGB(0x008, 1); } while (0)
; #define HALF2(Y0, Y1, alY, b) do { PVL(b); const float pm_ = max32(Y0, Y1); adjustSM(Y0, Y1, nm, alY, pm_); SBAR(); \
;     PVM(); exp16(Y0); asm volatile("" : "+v"(Y0)); \
;     SGB(0x008, 1); SGB(0x400, 3); SGB(0x008, 1); SGB(0x400, 3); SGB(0x008, 1); SGB(0x400, 3); SGB(0x008, 1); SGB(0x400, 3); SGB(0x008, 1); SGB(0x400, 4); SBAR(); } while (0)
; __device__ __forceinline__ void body(const unsigned char* Q8b, const unsigned char* K8h, const unsigned char* VT8h, const bf16_t* Gb, bf16_t* Ob, int seq, char* lds, const int wid, ...
;     ...
;   for (int i = 0; i + 2 < NT; i += 2) {
;     SBAR(); QKT(pB0, pB1, (s0 + 1) & 3);
;     finishSM(pA0, pA1, pf); PIPE1(); SBAR();
;     DMA((s0 + 3) & 3, i + 3);
;     SBAR();
;     HALF2(pB0, pB1, alB, s0);
;     ...
;     { const int t4 = (i + 4 < NT) ? i + 4 : NT - 1; DMA(s0, t4); }
;     SBAR();
;     HALF2(pA0, pA1, alA, (s0 + 1) & 3);
;     WAITV(2);
;     RESC(alA); BAR();
;     s0 = (s0 + 2) & 3;
;   }
.LgB_380:
	s_waitcnt vmcnt(2) lgkmcnt(0)
	s_barrier
	v_mfma_scale_f32_32x32x64_f8f6f4 v[64:79], v[2:9], v[194:201], v[64:79], v240, v240 op_sel_hi:[0,0,0]
	v_exp_f32_e32 v144, v160
	v_exp_f32_e32 v145, v161
	v_exp_f32_e32 v146, v162
	v_mfma_scale_f32_32x32x64_f8f6f4 v[48:63], v[2:9], v[148:155], v[48:63], v240, v240 op_sel_hi:[0,0,0]
	v_exp_f32_e32 v147, v163
	v_exp_f32_e32 v148, v164
	v_exp_f32_e32 v149, v165
	v_mfma_scale_f32_32x32x64_f8f6f4 v[32:47], v[2:9], v[136:143], v[32:47], v240, v240 op_sel_hi:[0,0,0]
	v_exp_f32_e32 v150, v166
	v_exp_f32_e32 v151, v167
	v_exp_f32_e32 v152, v168
	v_mfma_scale_f32_32x32x64_f8f6f4 v[16:31], v[2:9], v[128:135], v[16:31], v240, v240 op_sel_hi:[0,0,0]
	v_exp_f32_e32 v153, v169
	v_exp_f32_e32 v154, v170
	v_exp_f32_e32 v155, v171
	v_mfma_scale_f32_32x32x64_f8f6f4 v[80:95], v[2:9], v[228:235], v[80:95], v240, v240 op_sel_hi:[0,0,0]
	v_exp_f32_e32 v156, v172
	v_exp_f32_e32 v157, v173
	v_exp_f32_e32 v158, v174
	v_exp_f32_e32 v159, v175
	s_cmp_lg_u32 s93, 0
	s_cbranch_scc1 .Lr2_LgB
.LgB_373:
	s_add_i32 s45, s45, 2
	s_add_u32 s100, s100, 0x4000
	s_addc_u32 s101, s101, 0
	s_add_u32 s98, s98, 0x8000
	s_addc_u32 s99, s99, 0
	s_cmpk_gt_u32 s45, 0x7d
	s_cbranch_scc1 .LBB0_385
.LgBc2_374:
	ds_read_b128 v[2:5], v242 offset:57344
	ds_read_b128 v[6:9], v243 offset:57344
	ds_read_b128 v[128:131], v242 offset:61440
	ds_read_b128 v[132:135], v243 offset:61440
	ds_read_b128 v[194:197], v244 offset:57344
	ds_read_b128 v[198:201], v245 offset:57344
	ds_read_b128 v[246:249], v244 offset:61440
	ds_read_b128 v[250:253], v245 offset:61440
	v_exp_f32_e32 v1, v112
	v_exp_f32_e32 v10, v113
	v_exp_f32_e32 v11, v114
	v_exp_f32_e32 v12, v115
	s_waitcnt lgkmcnt(6)
	s_setprio 1
	v_mfma_scale_f32_32x32x64_f8f6f4 v[160:175], v[2:9], v[176:183], v[96:111], v240, v239 op_sel_hi:[0,0,0]
	v_exp_f32_e32 v6, v116
	v_exp_f32_e32 v7, v117
	v_exp_f32_e32 v8, v118
	v_exp_f32_e32 v9, v119
	v_cvt_pk_fp8_f32 v5, v6, v7
	v_cvt_pk_fp8_f32 v3, v1, v10
	v_cvt_pk_fp8_f32 v5, v8, v9 op_sel:[0,0,1]
	s_waitcnt lgkmcnt(4)
	v_mfma_scale_f32_32x32x64_f8f6f4 v[128:143], v[128:135], v[176:183], v[96:111], v240, v239 op_sel_hi:[0,0,0]
	v_exp_f32_e32 v13, v120
	v_exp_f32_e32 v14, v121
	v_exp_f32_e32 v15, v122
	v_exp_f32_e32 v112, v123
	v_cvt_pk_fp8_f32 v2, v144, v145
	v_cvt_pk_fp8_f32 v4, v148, v149
	v_cvt_pk_fp8_f32 v6, v152, v153
	v_cvt_pk_fp8_f32 v7, v13, v14
	v_cvt_pk_fp8_f32 v8, v156, v157
	v_cvt_pk_fp8_f32 v2, v146, v147 op_sel:[0,0,1]
	v_cvt_pk_fp8_f32 v3, v11, v12 op_sel:[0,0,1]
	v_cvt_pk_fp8_f32 v4, v150, v151 op_sel:[0,0,1]
	v_cvt_pk_fp8_f32 v6, v154, v155 op_sel:[0,0,1]
	v_cvt_pk_fp8_f32 v7, v15, v112 op_sel:[0,0,1]
	v_cvt_pk_fp8_f32 v8, v158, v159 op_sel:[0,0,1]
	s_waitcnt lgkmcnt(2)
	v_mfma_scale_f32_32x32x64_f8f6f4 v[160:175], v[194:201], v[184:191], v[160:175], v240, v239 op_sel_hi:[0,0,0]
	v_exp_f32_e32 v113, v124
	v_exp_f32_e32 v114, v125
	v_exp_f32_e32 v1, v126
	v_exp_f32_e32 v10, v127
	v_cvt_pk_fp8_f32 v9, v113, v114
	s_waitcnt lgkmcnt(0)
	v_cvt_pk_fp8_f32 v9, v1, v10 op_sel:[0,0,1]
	v_mfma_scale_f32_32x32x64_f8f6f4 v[128:143], v[246:253], v[184:191], v[128:143], v240, v239 op_sel_hi:[0,0,0]
	s_setprio 0
	s_add_i32 m0, s68, 0xa000
	s_nop 0
	global_load_lds_dwordx4 v192, s[98:99]
	s_add_i32 m0, s68, 0x2000
	s_nop 0
	global_load_lds_dwordx4 v193, s[100:101]
	ds_read_b128 v[194:197], v254 offset:16384
	ds_read_b128 v[148:151], v254 offset:18432
	ds_read_b128 v[198:201], v255 offset:16384
	ds_read_b128 v[152:155], v255 offset:18432
	ds_read_b128 v[120:123], v254 offset:20480
	ds_read_b128 v[112:115], v254 offset:22528
	ds_read_b128 v[124:127], v255 offset:20480
	ds_read_b128 v[116:119], v255 offset:22528
	v_max_f32_e32 v1, v160, v161
	v_max3_f32 v1, v1, v162, v163
	v_max3_f32 v1, v1, v164, v165
	v_max3_f32 v1, v1, v166, v167
	v_max3_f32 v1, v1, v168, v169
	v_max3_f32 v1, v1, v170, v171
	v_max3_f32 v1, v1, v172, v173
	v_max3_f32 v1, v1, v174, v175
	v_max3_f32 v1, v1, v128, v129
	v_max3_f32 v1, v1, v130, v131
	v_max3_f32 v1, v1, v132, v133
	v_max3_f32 v1, v1, v134, v135
	v_max3_f32 v1, v1, v136, v137
	v_max3_f32 v1, v1, v138, v139
	v_max3_f32 v1, v1, v140, v141
	v_max3_f32 v1, v1, v142, v143
	v_cmp_lt_f32_e32 vcc, s80, v1
	s_cbranch_vccnz .LgBc2_383
